# attention epilogue: wait for the first gate row moved below the LDS staging (staging overlaps the gate/prefetch load latency)
# speedup vs baseline: 1.0103x; 1.0103x over previous
.LBB0_1417:
	v_cmp_gt_u32_e32 vcc, 32, v188
	s_and_saveexec_b64 s[2:3], vcc
	v_lshl_add_u32 v44, v188, 2, s97
	ds_write_b32 v44, v43 offset:128
	s_or_b64 exec, exec, s[2:3]
	s_waitcnt lgkmcnt(0)
	ds_read_b128 v[44:47], v196 offset:128
	v_mov_b32_e32 v48, v80
	v_mov_b32_e32 v49, v96
	v_lshlrev_b32_e32 v43, 1, v193
	v_mov_b32_e32 v96, v81
	s_waitcnt lgkmcnt(0)
	v_rcp_f32_e32 v44, v44
	v_lshl_add_u64 v[40:41], s[30:31], 0, v[40:41]
	v_pk_mul_f32 v[48:49], v[48:49], v[44:45] op_sel_hi:[1,0]
	v_lshl_add_u64 v[40:41], v[40:41], 0, s[6:7]
	v_cvt_pk_bf16_f32 v44, v48, v49
	v_lshlrev_b32_e32 v48, 9, v192
	v_add3_u32 v43, s74, v43, v48
	ds_write_b16 v43, v44
	ds_write_b16_d16_hi v43, v44 offset:64
	v_rcp_f32_e32 v44, v45
	v_mov_b32_e32 v48, v82
	v_mov_b32_e32 v49, v98
	v_mov_b32_e32 v98, v83
	v_pk_mul_f32 v[44:45], v[96:97], v[44:45] op_sel_hi:[1,0]
	v_lshl_add_u64 v[40:41], v[40:41], 0, v[112:113]
	v_cvt_pk_bf16_f32 v44, v44, v45
	ds_write_b16 v43, v44 offset:128
	ds_write_b16_d16_hi v43, v44 offset:192
	v_rcp_f32_e32 v44, v46
	s_andn2_b64 vcc, exec, s[60:61]
	s_mov_b64 s[34:35], 0
	v_pk_mul_f32 v[44:45], v[48:49], v[44:45] op_sel_hi:[1,0]
	s_nop 0
	v_cvt_pk_bf16_f32 v44, v44, v45
	ds_write_b16 v43, v44 offset:256
	ds_write_b16_d16_hi v43, v44 offset:320
	v_rcp_f32_e32 v44, v47
	v_mov_b32_e32 v48, v84
	v_mov_b32_e32 v49, v100
	v_mov_b32_e32 v100, v85
	v_pk_mul_f32 v[44:45], v[98:99], v[44:45] op_sel_hi:[1,0]
	s_nop 0
	v_cvt_pk_bf16_f32 v44, v44, v45
	ds_write_b16 v43, v44 offset:384
	ds_write_b16_d16_hi v43, v44 offset:448
	ds_read_b128 v[44:47], v196 offset:160
	s_waitcnt lgkmcnt(0)
	v_rcp_f32_e32 v44, v44
	s_nop 0
	v_pk_mul_f32 v[48:49], v[48:49], v[44:45] op_sel_hi:[1,0]
	s_nop 0
	v_cvt_pk_bf16_f32 v44, v48, v49
	ds_write_b16 v43, v44 offset:1024
	ds_write_b16_d16_hi v43, v44 offset:1088
	v_rcp_f32_e32 v44, v45
	v_mov_b32_e32 v48, v86
	v_mov_b32_e32 v49, v102
	v_mov_b32_e32 v102, v87
	v_pk_mul_f32 v[44:45], v[100:101], v[44:45] op_sel_hi:[1,0]
	s_nop 0
	v_cvt_pk_bf16_f32 v44, v44, v45
	ds_write_b16 v43, v44 offset:1152
	ds_write_b16_d16_hi v43, v44 offset:1216
	v_rcp_f32_e32 v44, v46
	s_nop 0
	v_pk_mul_f32 v[44:45], v[48:49], v[44:45] op_sel_hi:[1,0]
	s_nop 0
	v_cvt_pk_bf16_f32 v44, v44, v45
	ds_write_b16 v43, v44 offset:1280
	ds_write_b16_d16_hi v43, v44 offset:1344
	v_rcp_f32_e32 v44, v47
	v_mov_b32_e32 v48, v88
	v_mov_b32_e32 v49, v104
	v_mov_b32_e32 v104, v89
	v_pk_mul_f32 v[44:45], v[102:103], v[44:45] op_sel_hi:[1,0]
	s_nop 0
	v_cvt_pk_bf16_f32 v44, v44, v45
	ds_write_b16 v43, v44 offset:1408
	ds_write_b16_d16_hi v43, v44 offset:1472
	ds_read_b128 v[44:47], v196 offset:192
	s_waitcnt lgkmcnt(0)
	v_rcp_f32_e32 v44, v44
	s_nop 0
	v_pk_mul_f32 v[48:49], v[48:49], v[44:45] op_sel_hi:[1,0]
	s_nop 0
	v_cvt_pk_bf16_f32 v44, v48, v49
	ds_write_b16 v43, v44 offset:2048
	ds_write_b16_d16_hi v43, v44 offset:2112
	v_rcp_f32_e32 v44, v45
	v_mov_b32_e32 v48, v90
	v_mov_b32_e32 v49, v106
	v_mov_b32_e32 v106, v91
	v_pk_mul_f32 v[44:45], v[104:105], v[44:45] op_sel_hi:[1,0]
	s_nop 0
	v_cvt_pk_bf16_f32 v44, v44, v45
	ds_write_b16 v43, v44 offset:2176
	ds_write_b16_d16_hi v43, v44 offset:2240
	v_rcp_f32_e32 v44, v46
	s_nop 0
	v_pk_mul_f32 v[44:45], v[48:49], v[44:45] op_sel_hi:[1,0]
	s_nop 0
	v_cvt_pk_bf16_f32 v44, v44, v45
	ds_write_b16 v43, v44 offset:2304
	ds_write_b16_d16_hi v43, v44 offset:2368
	v_rcp_f32_e32 v44, v47
	v_mov_b32_e32 v48, v92
	v_mov_b32_e32 v49, v108
	v_mov_b32_e32 v108, v93
	v_pk_mul_f32 v[44:45], v[106:107], v[44:45] op_sel_hi:[1,0]
	s_nop 0
	v_cvt_pk_bf16_f32 v44, v44, v45
	ds_write_b16 v43, v44 offset:2432
	ds_write_b16_d16_hi v43, v44 offset:2496
	ds_read_b128 v[44:47], v196 offset:224
	s_waitcnt lgkmcnt(0)
	v_rcp_f32_e32 v44, v44
	s_nop 0
	v_pk_mul_f32 v[48:49], v[48:49], v[44:45] op_sel_hi:[1,0]
	s_nop 0
	v_cvt_pk_bf16_f32 v44, v48, v49
	ds_write_b16 v43, v44 offset:3072
	ds_write_b16_d16_hi v43, v44 offset:3136
	v_rcp_f32_e32 v44, v45
	v_mov_b32_e32 v48, v94
	v_mov_b32_e32 v49, v110
	v_mov_b32_e32 v110, v95
	v_pk_mul_f32 v[44:45], v[108:109], v[44:45] op_sel_hi:[1,0]
	s_nop 0
	v_cvt_pk_bf16_f32 v44, v44, v45
	ds_write_b16 v43, v44 offset:3200
	ds_write_b16_d16_hi v43, v44 offset:3264
	v_rcp_f32_e32 v44, v46
	s_nop 0
	v_pk_mul_f32 v[44:45], v[48:49], v[44:45] op_sel_hi:[1,0]
	s_nop 0
	v_cvt_pk_bf16_f32 v44, v44, v45
	ds_write_b16 v43, v44 offset:3328
	ds_write_b16_d16_hi v43, v44 offset:3392
	v_rcp_f32_e32 v44, v47
	s_nop 0
	v_pk_mul_f32 v[44:45], v[110:111], v[44:45] op_sel_hi:[1,0]
	s_nop 0
	v_cvt_pk_bf16_f32 v44, v44, v45
	ds_write_b16 v43, v44 offset:3456
	ds_write_b16_d16_hi v43, v44 offset:3520
	s_waitcnt vmcnt(3)
	v_lshlrev_b32_e32 v50, 16, v36
	v_and_b32_e32 v51, 0xffff0000, v36
	v_add_u32_e32 v43, s74, v112
	s_waitcnt lgkmcnt(0)
	v_lshl_add_u32 v44, v42, 7, v43
	ds_read_b128 v[44:47], v44
	s_waitcnt lgkmcnt(0)
	v_lshlrev_b32_e32 v48, 16, v44
	v_and_b32_e32 v49, 0xffff0000, v44
	v_pk_mul_f32 v[48:49], v[50:51], v[48:49]
	v_lshlrev_b32_e32 v44, 16, v45
	v_cvt_pk_bf16_f32 v36, v48, v49
	v_and_b32_e32 v45, 0xffff0000, v45
	v_lshlrev_b32_e32 v48, 16, v37
	v_and_b32_e32 v49, 0xffff0000, v37
	v_pk_mul_f32 v[44:45], v[48:49], v[44:45]
	v_lshlrev_b32_e32 v48, 16, v38
	v_cvt_pk_bf16_f32 v37, v44, v45
	v_lshlrev_b32_e32 v44, 16, v46
	v_and_b32_e32 v45, 0xffff0000, v46
	v_and_b32_e32 v49, 0xffff0000, v38
	v_pk_mul_f32 v[44:45], v[48:49], v[44:45]
	v_lshlrev_b32_e32 v46, 16, v39
	v_cvt_pk_bf16_f32 v38, v44, v45
	v_lshlrev_b32_e32 v44, 16, v47
	v_and_b32_e32 v45, 0xffff0000, v47
	v_and_b32_e32 v47, 0xffff0000, v39
	v_pk_mul_f32 v[44:45], v[46:47], v[44:45]
	s_waitcnt vmcnt(2)
	v_lshlrev_b32_e32 v46, 16, v32
	v_cvt_pk_bf16_f32 v39, v44, v45
	global_store_dwordx4 v[40:41], v[36:39], off sc1
	s_nop 1
	v_add_u32_e32 v40, 8, v42
	v_lshl_add_u32 v36, v40, 7, v43
	ds_read_b128 v[36:39], v36
	v_and_b32_e32 v47, 0xffff0000, v32
	v_add_u32_e32 v40, s56, v40
	v_ashrrev_i32_e32 v41, 31, v40
	s_waitcnt lgkmcnt(0)
	v_lshlrev_b32_e32 v44, 16, v36
	v_and_b32_e32 v45, 0xffff0000, v36
	v_pk_mul_f32 v[44:45], v[46:47], v[44:45]
	v_lshlrev_b32_e32 v36, 16, v37
	v_cvt_pk_bf16_f32 v32, v44, v45
	v_and_b32_e32 v37, 0xffff0000, v37
	v_lshlrev_b32_e32 v44, 16, v33
	v_and_b32_e32 v45, 0xffff0000, v33
	v_pk_mul_f32 v[36:37], v[44:45], v[36:37]
	v_lshlrev_b32_e32 v44, 16, v34
	v_cvt_pk_bf16_f32 v33, v36, v37
	v_lshlrev_b32_e32 v36, 16, v38
	v_and_b32_e32 v37, 0xffff0000, v38
	v_and_b32_e32 v45, 0xffff0000, v34
	v_pk_mul_f32 v[36:37], v[44:45], v[36:37]
	v_lshlrev_b32_e32 v38, 16, v35
	v_cvt_pk_bf16_f32 v34, v36, v37
	v_lshlrev_b32_e32 v36, 16, v39
	v_and_b32_e32 v37, 0xffff0000, v39
	v_and_b32_e32 v39, 0xffff0000, v35
	v_pk_mul_f32 v[36:37], v[38:39], v[36:37]
	s_nop 0
	v_cvt_pk_bf16_f32 v35, v36, v37
	v_lshlrev_b64 v[36:37], 11, v[40:41]
	v_lshl_add_u64 v[36:37], s[30:31], 0, v[36:37]
	v_lshl_add_u64 v[36:37], v[36:37], 0, s[6:7]
	v_lshl_add_u64 v[36:37], v[36:37], 0, v[112:113]
	global_store_dwordx4 v[36:37], v[32:35], off sc1
	s_nop 1
	v_add_u32_e32 v36, 16, v42
	v_lshl_add_u32 v32, v36, 7, v43
	ds_read_b128 v[32:35], v32
	s_waitcnt vmcnt(3)
	v_lshlrev_b32_e32 v40, 16, v28
	v_and_b32_e32 v41, 0xffff0000, v28
	v_add_u32_e32 v36, s56, v36
	v_ashrrev_i32_e32 v37, 31, v36
	s_waitcnt lgkmcnt(0)
	v_lshlrev_b32_e32 v38, 16, v32
	v_and_b32_e32 v39, 0xffff0000, v32
	v_pk_mul_f32 v[38:39], v[40:41], v[38:39]
	v_lshlrev_b32_e32 v32, 16, v33
	v_cvt_pk_bf16_f32 v28, v38, v39
	v_and_b32_e32 v33, 0xffff0000, v33
	v_lshlrev_b32_e32 v38, 16, v29
	v_and_b32_e32 v39, 0xffff0000, v29
	v_pk_mul_f32 v[32:33], v[38:39], v[32:33]
	v_lshlrev_b32_e32 v38, 16, v30
	v_cvt_pk_bf16_f32 v29, v32, v33
	v_lshlrev_b32_e32 v32, 16, v34
	v_and_b32_e32 v33, 0xffff0000, v34
	v_and_b32_e32 v39, 0xffff0000, v30
	v_pk_mul_f32 v[32:33], v[38:39], v[32:33]
	v_lshlrev_b32_e32 v34, 16, v31
	v_cvt_pk_bf16_f32 v30, v32, v33
	v_lshlrev_b32_e32 v32, 16, v35
	v_and_b32_e32 v33, 0xffff0000, v35
	v_and_b32_e32 v35, 0xffff0000, v31
	v_pk_mul_f32 v[32:33], v[34:35], v[32:33]
	s_nop 0
	v_cvt_pk_bf16_f32 v31, v32, v33
	v_lshlrev_b64 v[32:33], 11, v[36:37]
	v_lshl_add_u64 v[32:33], s[30:31], 0, v[32:33]
	v_lshl_add_u64 v[32:33], v[32:33], 0, s[6:7]
	v_lshl_add_u64 v[32:33], v[32:33], 0, v[112:113]
	global_store_dwordx4 v[32:33], v[28:31], off sc1
	s_nop 1
	v_add_u32_e32 v32, 24, v42
	v_lshl_add_u32 v28, v32, 7, v43
	ds_read_b128 v[28:31], v28
	s_waitcnt vmcnt(3)
	v_lshlrev_b32_e32 v36, 16, v24
	v_and_b32_e32 v37, 0xffff0000, v24
	v_add_u32_e32 v32, s56, v32
	v_ashrrev_i32_e32 v33, 31, v32
	s_waitcnt lgkmcnt(0)
	v_lshlrev_b32_e32 v34, 16, v28
	v_and_b32_e32 v35, 0xffff0000, v28
	v_pk_mul_f32 v[34:35], v[36:37], v[34:35]
	v_lshlrev_b32_e32 v28, 16, v29
	v_cvt_pk_bf16_f32 v24, v34, v35
	v_and_b32_e32 v29, 0xffff0000, v29
	v_lshlrev_b32_e32 v34, 16, v25
	v_and_b32_e32 v35, 0xffff0000, v25
	v_pk_mul_f32 v[28:29], v[34:35], v[28:29]
	v_lshlrev_b32_e32 v34, 16, v26
	v_cvt_pk_bf16_f32 v25, v28, v29
	v_lshlrev_b32_e32 v28, 16, v30
	v_and_b32_e32 v29, 0xffff0000, v30
	v_and_b32_e32 v35, 0xffff0000, v26
	v_pk_mul_f32 v[28:29], v[34:35], v[28:29]
	v_lshlrev_b32_e32 v30, 16, v27
	v_cvt_pk_bf16_f32 v26, v28, v29
	v_lshlrev_b32_e32 v28, 16, v31
	v_and_b32_e32 v29, 0xffff0000, v31
	v_and_b32_e32 v31, 0xffff0000, v27
	v_pk_mul_f32 v[28:29], v[30:31], v[28:29]
	s_nop 0
	v_cvt_pk_bf16_f32 v27, v28, v29
	v_lshlrev_b64 v[28:29], 11, v[32:33]
	v_lshl_add_u64 v[28:29], s[30:31], 0, v[28:29]
	v_lshl_add_u64 v[28:29], v[28:29], 0, s[6:7]
	v_lshl_add_u64 v[28:29], v[28:29], 0, v[112:113]
	global_store_dwordx4 v[28:29], v[24:27], off sc1
	s_nop 1
	s_mov_b64 s[6:7], 0
	s_cbranch_vccnz .LBB0_1421
	s_waitcnt vmcnt(0) lgkmcnt(0)
	s_and_b64 s[34:35], s[4:5], exec

.LBB0_1503:
	s_movk_i32 s64, 0x2000
	v_cmp_gt_u32_e32 vcc, 32, v188
	s_and_saveexec_b64 s[2:3], vcc
	v_lshl_add_u32 v44, v188, 2, s97
	ds_write_b32 v44, v43 offset:128
	s_or_b64 exec, exec, s[2:3]
	s_waitcnt lgkmcnt(0)
	ds_read_b128 v[44:47], v172 offset:128
	v_mov_b32_e32 v48, v80
	v_mov_b32_e32 v49, v96
	v_lshlrev_b32_e32 v43, 1, v193
	v_mov_b32_e32 v96, v81
	s_waitcnt lgkmcnt(0)
	v_rcp_f32_e32 v44, v44
	v_lshl_add_u64 v[40:41], s[30:31], 0, v[40:41]
	v_pk_mul_f32 v[48:49], v[48:49], v[44:45] op_sel_hi:[1,0]
	v_lshl_add_u64 v[40:41], v[40:41], 0, s[4:5]
	v_cvt_pk_bf16_f32 v44, v48, v49
	v_lshlrev_b32_e32 v48, 9, v192
	v_add3_u32 v43, s74, v43, v48
	ds_write_b16 v43, v44
	ds_write_b16_d16_hi v43, v44 offset:64
	v_rcp_f32_e32 v44, v45
	v_mov_b32_e32 v48, v82
	v_mov_b32_e32 v49, v98
	v_mov_b32_e32 v98, v83
	v_pk_mul_f32 v[44:45], v[96:97], v[44:45] op_sel_hi:[1,0]
	v_lshl_add_u64 v[40:41], v[40:41], 0, v[112:113]
	v_cvt_pk_bf16_f32 v44, v44, v45
	ds_write_b16 v43, v44 offset:128
	ds_write_b16_d16_hi v43, v44 offset:192
	v_rcp_f32_e32 v44, v46
	s_andn2_b64 vcc, exec, s[60:61]
	v_pk_mul_f32 v[44:45], v[48:49], v[44:45] op_sel_hi:[1,0]
	s_nop 0
	v_cvt_pk_bf16_f32 v44, v44, v45
	ds_write_b16 v43, v44 offset:256
	ds_write_b16_d16_hi v43, v44 offset:320
	v_rcp_f32_e32 v44, v47
	v_mov_b32_e32 v48, v84
	v_mov_b32_e32 v49, v100
	v_mov_b32_e32 v100, v85
	v_pk_mul_f32 v[44:45], v[98:99], v[44:45] op_sel_hi:[1,0]
	s_nop 0
	v_cvt_pk_bf16_f32 v44, v44, v45
	ds_write_b16 v43, v44 offset:384
	ds_write_b16_d16_hi v43, v44 offset:448
	ds_read_b128 v[44:47], v172 offset:160
	s_waitcnt lgkmcnt(0)
	v_rcp_f32_e32 v44, v44
	s_nop 0
	v_pk_mul_f32 v[48:49], v[48:49], v[44:45] op_sel_hi:[1,0]
	s_nop 0
	v_cvt_pk_bf16_f32 v44, v48, v49
	ds_write_b16 v43, v44 offset:1024
	ds_write_b16_d16_hi v43, v44 offset:1088
	v_rcp_f32_e32 v44, v45
	v_mov_b32_e32 v48, v86
	v_mov_b32_e32 v49, v102
	v_mov_b32_e32 v102, v87
	v_pk_mul_f32 v[44:45], v[100:101], v[44:45] op_sel_hi:[1,0]
	s_nop 0
	v_cvt_pk_bf16_f32 v44, v44, v45
	ds_write_b16 v43, v44 offset:1152
	ds_write_b16_d16_hi v43, v44 offset:1216
	v_rcp_f32_e32 v44, v46
	s_nop 0
	v_pk_mul_f32 v[44:45], v[48:49], v[44:45] op_sel_hi:[1,0]
	s_nop 0
	v_cvt_pk_bf16_f32 v44, v44, v45
	ds_write_b16 v43, v44 offset:1280
	ds_write_b16_d16_hi v43, v44 offset:1344
	v_rcp_f32_e32 v44, v47
	v_mov_b32_e32 v48, v88
	v_mov_b32_e32 v49, v104
	v_mov_b32_e32 v104, v89
	v_pk_mul_f32 v[44:45], v[102:103], v[44:45] op_sel_hi:[1,0]
	s_nop 0
	v_cvt_pk_bf16_f32 v44, v44, v45
	ds_write_b16 v43, v44 offset:1408
	ds_write_b16_d16_hi v43, v44 offset:1472
	ds_read_b128 v[44:47], v172 offset:192
	s_waitcnt lgkmcnt(0)
	v_rcp_f32_e32 v44, v44
	s_nop 0
	v_pk_mul_f32 v[48:49], v[48:49], v[44:45] op_sel_hi:[1,0]
	s_nop 0
	v_cvt_pk_bf16_f32 v44, v48, v49
	ds_write_b16 v43, v44 offset:2048
	ds_write_b16_d16_hi v43, v44 offset:2112
	v_rcp_f32_e32 v44, v45
	v_mov_b32_e32 v48, v90
	v_mov_b32_e32 v49, v106
	v_mov_b32_e32 v106, v91
	v_pk_mul_f32 v[44:45], v[104:105], v[44:45] op_sel_hi:[1,0]
	s_nop 0
	v_cvt_pk_bf16_f32 v44, v44, v45
	ds_write_b16 v43, v44 offset:2176
	ds_write_b16_d16_hi v43, v44 offset:2240
	v_rcp_f32_e32 v44, v46
	s_nop 0
	v_pk_mul_f32 v[44:45], v[48:49], v[44:45] op_sel_hi:[1,0]
	s_nop 0
	v_cvt_pk_bf16_f32 v44, v44, v45
	ds_write_b16 v43, v44 offset:2304
	ds_write_b16_d16_hi v43, v44 offset:2368
	v_rcp_f32_e32 v44, v47
	v_mov_b32_e32 v48, v92
	v_mov_b32_e32 v49, v108
	v_mov_b32_e32 v108, v93
	v_pk_mul_f32 v[44:45], v[106:107], v[44:45] op_sel_hi:[1,0]
	s_nop 0
	v_cvt_pk_bf16_f32 v44, v44, v45
	ds_write_b16 v43, v44 offset:2432
	ds_write_b16_d16_hi v43, v44 offset:2496
	ds_read_b128 v[44:47], v172 offset:224
	s_waitcnt lgkmcnt(0)
	v_rcp_f32_e32 v44, v44
	s_nop 0
	v_pk_mul_f32 v[48:49], v[48:49], v[44:45] op_sel_hi:[1,0]
	s_nop 0
	v_cvt_pk_bf16_f32 v44, v48, v49
	ds_write_b16 v43, v44 offset:3072
	ds_write_b16_d16_hi v43, v44 offset:3136
	v_rcp_f32_e32 v44, v45
	v_mov_b32_e32 v48, v94
	v_mov_b32_e32 v49, v110
	v_mov_b32_e32 v110, v95
	v_pk_mul_f32 v[44:45], v[108:109], v[44:45] op_sel_hi:[1,0]
	s_nop 0
	v_cvt_pk_bf16_f32 v44, v44, v45
	ds_write_b16 v43, v44 offset:3200
	ds_write_b16_d16_hi v43, v44 offset:3264
	v_rcp_f32_e32 v44, v46
	s_nop 0
	v_pk_mul_f32 v[44:45], v[48:49], v[44:45] op_sel_hi:[1,0]
	s_nop 0
	v_cvt_pk_bf16_f32 v44, v44, v45
	ds_write_b16 v43, v44 offset:3328
	ds_write_b16_d16_hi v43, v44 offset:3392
	v_rcp_f32_e32 v44, v47
	s_nop 0
	v_pk_mul_f32 v[44:45], v[110:111], v[44:45] op_sel_hi:[1,0]
	s_nop 0
	v_cvt_pk_bf16_f32 v44, v44, v45
	ds_write_b16 v43, v44 offset:3456
	ds_write_b16_d16_hi v43, v44 offset:3520
	s_waitcnt vmcnt(3)
	v_lshlrev_b32_e32 v50, 16, v36
	v_and_b32_e32 v51, 0xffff0000, v36
	v_add_u32_e32 v43, s74, v112
	s_waitcnt lgkmcnt(0)
	v_lshl_add_u32 v44, v42, 7, v43
	ds_read_b128 v[44:47], v44
	s_waitcnt lgkmcnt(0)
	v_lshlrev_b32_e32 v48, 16, v44
	v_and_b32_e32 v49, 0xffff0000, v44
	v_pk_mul_f32 v[48:49], v[50:51], v[48:49]
	v_lshlrev_b32_e32 v44, 16, v45
	v_cvt_pk_bf16_f32 v36, v48, v49
	v_and_b32_e32 v45, 0xffff0000, v45
	v_lshlrev_b32_e32 v48, 16, v37
	v_and_b32_e32 v49, 0xffff0000, v37
	v_pk_mul_f32 v[44:45], v[48:49], v[44:45]
	v_lshlrev_b32_e32 v48, 16, v38
	v_cvt_pk_bf16_f32 v37, v44, v45
	v_lshlrev_b32_e32 v44, 16, v46
	v_and_b32_e32 v45, 0xffff0000, v46
	v_and_b32_e32 v49, 0xffff0000, v38
	v_pk_mul_f32 v[44:45], v[48:49], v[44:45]
	v_lshlrev_b32_e32 v46, 16, v39
	v_cvt_pk_bf16_f32 v38, v44, v45
	v_lshlrev_b32_e32 v44, 16, v47
	v_and_b32_e32 v45, 0xffff0000, v47
	v_and_b32_e32 v47, 0xffff0000, v39
	v_pk_mul_f32 v[44:45], v[46:47], v[44:45]
	s_waitcnt vmcnt(2)
	v_lshlrev_b32_e32 v46, 16, v32
	v_cvt_pk_bf16_f32 v39, v44, v45
	global_store_dwordx4 v[40:41], v[36:39], off sc1
	s_nop 1
	v_add_u32_e32 v40, 8, v42
	v_lshl_add_u32 v36, v40, 7, v43
	ds_read_b128 v[36:39], v36
	v_and_b32_e32 v47, 0xffff0000, v32
	v_add_u32_e32 v40, s56, v40
	v_ashrrev_i32_e32 v41, 31, v40
	s_waitcnt lgkmcnt(0)
	v_lshlrev_b32_e32 v44, 16, v36
	v_and_b32_e32 v45, 0xffff0000, v36
	v_pk_mul_f32 v[44:45], v[46:47], v[44:45]
	v_lshlrev_b32_e32 v36, 16, v37
	v_cvt_pk_bf16_f32 v32, v44, v45
	v_and_b32_e32 v37, 0xffff0000, v37
	v_lshlrev_b32_e32 v44, 16, v33
	v_and_b32_e32 v45, 0xffff0000, v33
	v_pk_mul_f32 v[36:37], v[44:45], v[36:37]
	v_lshlrev_b32_e32 v44, 16, v34
	v_cvt_pk_bf16_f32 v33, v36, v37
	v_lshlrev_b32_e32 v36, 16, v38
	v_and_b32_e32 v37, 0xffff0000, v38
	v_and_b32_e32 v45, 0xffff0000, v34
	v_pk_mul_f32 v[36:37], v[44:45], v[36:37]
	v_lshlrev_b32_e32 v38, 16, v35
	v_cvt_pk_bf16_f32 v34, v36, v37
	v_lshlrev_b32_e32 v36, 16, v39
	v_and_b32_e32 v37, 0xffff0000, v39
	v_and_b32_e32 v39, 0xffff0000, v35
	v_pk_mul_f32 v[36:37], v[38:39], v[36:37]
	s_nop 0
	v_cvt_pk_bf16_f32 v35, v36, v37
	v_lshlrev_b64 v[36:37], 11, v[40:41]
	v_lshl_add_u64 v[36:37], s[30:31], 0, v[36:37]
	v_lshl_add_u64 v[36:37], v[36:37], 0, s[4:5]
	v_lshl_add_u64 v[36:37], v[36:37], 0, v[112:113]
	global_store_dwordx4 v[36:37], v[32:35], off sc1
	s_nop 1
	v_add_u32_e32 v36, 16, v42
	v_lshl_add_u32 v32, v36, 7, v43
	ds_read_b128 v[32:35], v32
	s_waitcnt vmcnt(3)
	v_lshlrev_b32_e32 v40, 16, v28
	v_and_b32_e32 v41, 0xffff0000, v28
	v_add_u32_e32 v36, s56, v36
	v_ashrrev_i32_e32 v37, 31, v36
	s_waitcnt lgkmcnt(0)
	v_lshlrev_b32_e32 v38, 16, v32
	v_and_b32_e32 v39, 0xffff0000, v32
	v_pk_mul_f32 v[38:39], v[40:41], v[38:39]
	v_lshlrev_b32_e32 v32, 16, v33
	v_cvt_pk_bf16_f32 v28, v38, v39
	v_and_b32_e32 v33, 0xffff0000, v33
	v_lshlrev_b32_e32 v38, 16, v29
	v_and_b32_e32 v39, 0xffff0000, v29
	v_pk_mul_f32 v[32:33], v[38:39], v[32:33]
	v_lshlrev_b32_e32 v38, 16, v30
	v_cvt_pk_bf16_f32 v29, v32, v33
	v_lshlrev_b32_e32 v32, 16, v34
	v_and_b32_e32 v33, 0xffff0000, v34
	v_and_b32_e32 v39, 0xffff0000, v30
	v_pk_mul_f32 v[32:33], v[38:39], v[32:33]
	v_lshlrev_b32_e32 v34, 16, v31
	v_cvt_pk_bf16_f32 v30, v32, v33
	v_lshlrev_b32_e32 v32, 16, v35
	v_and_b32_e32 v33, 0xffff0000, v35
	v_and_b32_e32 v35, 0xffff0000, v31
	v_pk_mul_f32 v[32:33], v[34:35], v[32:33]
	s_nop 0
	v_cvt_pk_bf16_f32 v31, v32, v33
	v_lshlrev_b64 v[32:33], 11, v[36:37]
	v_lshl_add_u64 v[32:33], s[30:31], 0, v[32:33]
	v_lshl_add_u64 v[32:33], v[32:33], 0, s[4:5]
	v_lshl_add_u64 v[32:33], v[32:33], 0, v[112:113]
	global_store_dwordx4 v[32:33], v[28:31], off sc1
	s_nop 1
	v_add_u32_e32 v32, 24, v42
	v_lshl_add_u32 v28, v32, 7, v43
	ds_read_b128 v[28:31], v28
	s_waitcnt vmcnt(3)
	v_lshlrev_b32_e32 v36, 16, v24
	v_and_b32_e32 v37, 0xffff0000, v24
	v_add_u32_e32 v32, s56, v32
	v_ashrrev_i32_e32 v33, 31, v32
	s_waitcnt lgkmcnt(0)
	v_lshlrev_b32_e32 v34, 16, v28
	v_and_b32_e32 v35, 0xffff0000, v28
	v_pk_mul_f32 v[34:35], v[36:37], v[34:35]
	v_lshlrev_b32_e32 v28, 16, v29
	v_cvt_pk_bf16_f32 v24, v34, v35
	v_and_b32_e32 v29, 0xffff0000, v29
	v_lshlrev_b32_e32 v34, 16, v25
	v_and_b32_e32 v35, 0xffff0000, v25
	v_pk_mul_f32 v[28:29], v[34:35], v[28:29]
	v_lshlrev_b32_e32 v34, 16, v26
	v_cvt_pk_bf16_f32 v25, v28, v29
	v_lshlrev_b32_e32 v28, 16, v30
	v_and_b32_e32 v29, 0xffff0000, v30
	v_and_b32_e32 v35, 0xffff0000, v26
	v_pk_mul_f32 v[28:29], v[34:35], v[28:29]
	v_lshlrev_b32_e32 v30, 16, v27
	v_cvt_pk_bf16_f32 v26, v28, v29
	v_lshlrev_b32_e32 v28, 16, v31
	v_and_b32_e32 v29, 0xffff0000, v31
	v_and_b32_e32 v31, 0xffff0000, v27
	v_pk_mul_f32 v[28:29], v[30:31], v[28:29]
	s_nop 0
	v_cvt_pk_bf16_f32 v27, v28, v29
	v_lshlrev_b64 v[28:29], 11, v[32:33]
	v_lshl_add_u64 v[28:29], s[30:31], 0, v[28:29]
	v_lshl_add_u64 v[28:29], v[28:29], 0, s[4:5]
	v_lshl_add_u64 v[28:29], v[28:29], 0, v[112:113]
	global_store_dwordx4 v[28:29], v[24:27], off sc1
	s_nop 1
	s_cbranch_vccnz .LBB0_1507
	s_waitcnt vmcnt(0) lgkmcnt(0)
	s_andn2_b64 s[2:3], s[34:35], exec
	s_and_b64 s[4:5], s[10:11], exec
	s_or_b64 s[34:35], s[2:3], s[4:5]
